# v22 + attention loop: pre-shifted V-address register and merged K-address add (3 fewer VALU per super-tile)
# speedup vs baseline: 1.0066x; 1.0004x over previous
; DI void attn_phase(const Params& p, unsigned char* smem) {
;     ...
;         const int kr0 = tid / 12, kr1 = (tid + 512) / 12, kr2 = (tid + 1024) / 12;
;         const int kh0 = tid - kr0 * 12, kh1 = tid + 512 - kr1 * 12, kh2 = tid + 1024 - kr2 * 12;
;         const int kd0 = kr0 * KST + kh0 * 8, kd1 = kr1 * KST + kh1 * 8, kd2 = kr2 * KST + kh2 * 8;
;         const int ko0 = kr0 * 768 + kh0 * 8, ko1 = kr1 * 768 + kh1 * 8, ko2 = kr2 * 768 + kh2 * 8;
;         const bf16_t* kbase = KB + (size_t)kvbase * 768 + h * 96;
;         const int vch = tid & 15, vdv0 = tid >> 4, vdv1 = vdv0 + 32;
;         const int vd0 = 128 * KST + vdv0 * VST + vch * 8, vd1 = 128 * KST + vdv1 * VST + vch * 8;
;         const bf16_t* vbase = VT + vb + (size_t)(h * 64) * Ts + vch * 8;
;         const size_t vo0 = (size_t)vdv0 * Ts, vo1 = (size_t)vdv1 * Ts;
;         const int nst = (ntiles + 1) >> 1;
;         unsigned zz = 0; asm volatile("" : "+v"(zz));
;         uint4 rk0, rk1 = make_uint4(zz, zz, zz, zz), rk2 = rk1, rv0 = rk1, rv1 = rk1;
.LBB0_902:
	s_or_b64 exec, exec, s[0:1]
	s_waitcnt lgkmcnt(0)
	v_mov_b32_e32 v0, v250
	s_barrier
	s_mov_b32 s0, 0x2aaaaaab
	v_ashrrev_i32_e32 v1, 6, v0
	s_waitcnt vmcnt(1)
	v_and_b32_e32 v9, 15, v0
	v_cmp_gt_i32_e32 vcc, 2, v1
	v_ashrrev_i32_e32 v2, 7, v0
	v_lshl_or_b32 v173, v1, 5, v9
	v_mul_hi_i32 v1, v0, s0
	v_add_u32_e32 v171, 1, v2
	v_lshrrev_b32_e32 v2, 31, v1
	v_ashrrev_i32_e32 v1, 1, v1
	v_add_u32_e32 v1, v1, v2
	v_add_u32_e32 v2, 0x200, v0
	v_mul_hi_i32 v3, v2, s0
	s_waitcnt vmcnt(1)
	v_lshrrev_b32_e32 v4, 31, v3
	v_ashrrev_i32_e32 v3, 1, v3
	v_add_u32_e32 v8, v3, v4
	v_add_u32_e32 v4, 0x400, v0
	v_mul_hi_i32 v3, v4, s0
	v_lshrrev_b32_e32 v5, 31, v3
	v_ashrrev_i32_e32 v3, 1, v3
	v_add_u32_e32 v11, v3, v5
	v_mad_u64_u32 v[6:7], s[0:1], v1, -12, v[0:1]
	v_mad_u64_u32 v[2:3], s[0:1], v8, -12, v[2:3]
	v_mad_u64_u32 v[4:5], s[0:1], v11, -12, v[4:5]
	s_movk_i32 s0, 0x70
	s_nop 0
	v_mul_lo_u32 v3, v1, s0
	v_lshl_add_u32 v168, v6, 3, v3
	v_mul_lo_u32 v3, v8, s0
	v_lshl_add_u32 v170, v2, 3, v3
	v_mul_lo_u32 v2, v11, s0
	v_cndmask_b32_e64 v169, 0, 33, vcc
	v_lshl_add_u32 v172, v4, 3, v2
	s_movk_i32 s6, 0x290
	v_mad_u64_u32 v[2:3], s[0:1], v1, s6, v[168:169]
	v_mad_u64_u32 v[4:5], s[0:1], v8, s6, v[170:171]
	v_mad_u64_u32 v[6:7], s[0:1], v11, s6, v[172:173]
	v_ashrrev_i32_e32 v174, 4, v0
	s_movk_i32 s0, 0x88
	v_mul_lo_u32 v1, v174, s0
	s_movk_i32 s0, 0x100
	v_bfe_u32 v10, v0, 4, 2
	v_cmp_gt_i32_e64 s[36:37], s0, v0
	v_mov_b32_e32 v0, 0x1100
	s_movk_i32 s0, 0x110
	v_lshlrev_b32_e32 v8, 3, v9
	v_mad_u32_u24 v220, v9, s0, v0
	v_mov_b32_e32 v0, 0x2200
	v_or_b32_e32 v3, 0x3800, v8
	v_mad_u32_u24 v221, v9, s0, v0
	v_mov_b32_e32 v0, 0x3300
	v_lshlrev_b32_e32 v212, 3, v10
	v_lshlrev_b32_e32 v164, 4, v10
	v_add_u32_e32 v11, v3, v1
	v_add_u32_e32 v12, 0x1100, v1
	v_mul_u32_u24_e32 v219, 0x110, v9
	v_mad_u32_u24 v222, v9, s0, v0
	v_readlane_b32 s0, v254, 54
	v_mov_b32_e32 v165, v213
	v_add_u32_e32 v13, v3, v12
	v_ashrrev_i32_e32 v3, 31, v2
	v_ashrrev_i32_e32 v5, 31, v4
	v_ashrrev_i32_e32 v7, 31, v6
	v_add_u32_e32 v215, v8, v12
	v_lshlrev_b32_e32 v217, 3, v10
	v_mul_u32_u24_e32 v218, 0xe0, v9
	v_add_u32_e32 v0, 16, v164
	v_add3_u32 v223, 16, v219, v212
	v_lshl_add_u32 v227, v11, 1, s0
	v_mov_b64_e32 v[10:11], 0x16d20000
	s_mov_b32 s22, s96
	s_mov_b32 s23, 0
	v_lshl_add_u64 v[166:167], s[76:77], 0, v[164:165]
	v_cmp_gt_u32_e64 s[38:39], 8, v9
	v_lshl_add_u32 v165, v168, 1, 16
	v_lshl_add_u32 v175, v170, 1, 16
	v_lshl_add_u32 v156, v172, 1, 16
	v_add_u32_e32 v214, v8, v1
	v_lshl_add_u32 v216, v215, 1, 16
	v_lshl_add_u64 v[176:177], s[60:61], 0, v[212:213]
	v_add_u32_e32 v224, 0x1100, v223
	v_add_u32_e32 v225, 0x2200, v223
	v_add_u32_e32 v226, 0x3300, v223
	v_lshl_add_u32 v228, v13, 1, s0
	v_lshl_add_u64 v[178:179], v[2:3], 1, v[10:11]
	v_lshl_add_u64 v[180:181], v[4:5], 1, v[10:11]
	v_lshl_add_u64 v[182:183], v[6:7], 1, v[10:11]
	v_lshlrev_b32_e32 v212, 1, v8
	v_lshlrev_b64 v[184:185], 1, v[2:3]
	v_lshlrev_b64 v[186:187], 1, v[4:5]
	v_lshlrev_b64 v[188:189], 1, v[6:7]
	v_add_u32_e32 v229, v0, v218
	s_mov_b32 s6, 0
	s_mov_b32 s26, 0
	s_branch .LBB0_905

; #define MFMA16(a, b, c) __builtin_amdgcn_mfma_f32_16x16x32_bf16((a), (b), (c), 0, 0, 0)
; DI void attn_phase(const Params& p, unsigned char* smem) {
;     ...
;                 if (2 * st_ + hf < wtiles) {
;                     const bf16_t* sK = sbuf + cur * BUF + hf * 64 * KST; const bf16_t* sV = sbuf + cur * BUF + 128 * KST + hf * 64;
;                     bf16x8 kf[4][3];
; #pragma unroll
;                     for (int kk = 0; kk < 4; ++kk)
; #pragma unroll
;                         for (int s = 0; s < 3; ++s) kf[kk][s] = *(const bf16x8*)(sK + (16 * kk + fr) * KST + 32 * s + 8 * g);
; #pragma unroll
;                     for (int qs = 0; qs < 2; ++qs) {
;                         f32x4 st[4];
;                         const float nm = -mrow[qs];
; #pragma unroll
;                         for (int kk = 0; kk < 4; ++kk) {
;                             st[kk] = (f32x4){nm, nm, nm, nm};
; #pragma unroll
;                             for (int s = 0; s < 3; ++s) st[kk] = MFMA16(kf[kk][s], qf[qs][s], st[kk]);
;                         }
;                         float mx = fmaxf(fmaxf(st[0][0], st[0][1]), fmaxf(st[0][2], st[0][3]));
; #pragma unroll
;                         for (int kk = 1; kk < 4; ++kk) mx = fmaxf(mx, fmaxf(fmaxf(st[kk][0], st[kk][1]), fmaxf(st[kk][2], st[kk][3])));
;                         const bool first = (st_ == 0 && hf == 0);
;                         if (first || __any(mx > 6.f)) {
;                             mx = fmaxf(mx, __shfl_xor(mx, 16)); mx = fmaxf(mx, __shfl_xor(mx, 32));
;                             const float shift = first ? mx : fmaxf(mx, 0.f);
;                             const float al = first ? 1.f : __builtin_amdgcn_exp2f(-shift);
;                             mrow[qs] += shift; lrow[qs] *= al;
; #pragma unroll
;                             for (int dt = 0; dt < 4; ++dt) ot[dt][qs] *= al;
; #pragma unroll
;                             for (int kk = 0; kk < 4; ++kk)
; #pragma unroll
;                                 for (int e = 0; e < 4; ++e) st[kk][e] -= shift;
;                         }
.LBB0_943:
	s_add_i32 s14, s43, -1
	s_and_b32 s18, s14, 1
	s_mul_i32 s14, s18, 0xb400
	s_add_i32 s19, s14, 16
	v_cmp_lt_i32_e32 vcc, s44, v230
	v_add3_u32 v231, s19, v164, v218
	s_and_saveexec_b64 s[14:15], vcc
	s_cbranch_execz .LBB0_949
	v_xor_b32_e32 v132, 0x80000000, v203
	v_mov_b32_e32 v133, v132
	v_mov_b32_e32 v134, v132
	v_mov_b32_e32 v135, v132
	ds_read_b128 v[112:115], v231
	ds_read_b128 v[116:119], v231 offset:64
	ds_read_b128 v[120:123], v231 offset:128
	ds_read_b128 v[100:103], v231 offset:3584
	ds_read_b128 v[104:107], v231 offset:3648
	ds_read_b128 v[108:111], v231 offset:3712
	ds_read_b128 v[96:99], v231 offset:7168
	ds_read_b128 v[92:95], v231 offset:7232
	ds_read_b128 v[88:91], v231 offset:7296
	ds_read_b128 v[84:87], v231 offset:10752
	ds_read_b128 v[80:83], v231 offset:10816
	ds_read_b128 v[76:79], v231 offset:10880
	s_waitcnt lgkmcnt(11)
	v_mfma_f32_16x16x32_bf16 v[124:127], v[112:115], v[4:7], v[132:135]
	s_waitcnt lgkmcnt(8)
	v_mfma_f32_16x16x32_bf16 v[128:131], v[100:103], v[4:7], v[132:135]
	v_mfma_f32_16x16x32_bf16 v[124:127], v[116:119], v[0:3], v[124:127]
	s_waitcnt lgkmcnt(5)
	v_mfma_f32_16x16x32_bf16 v[136:139], v[96:99], v[4:7], v[132:135]
	s_waitcnt lgkmcnt(2)
	v_mfma_f32_16x16x32_bf16 v[132:135], v[84:87], v[4:7], v[132:135]
	v_mfma_f32_16x16x32_bf16 v[128:131], v[104:107], v[0:3], v[128:131]
	v_mfma_f32_16x16x32_bf16 v[124:127], v[120:123], v[12:15], v[124:127]
	s_waitcnt lgkmcnt(1)
	v_mfma_f32_16x16x32_bf16 v[132:135], v[80:83], v[0:3], v[132:135]
	v_mfma_f32_16x16x32_bf16 v[136:139], v[92:95], v[0:3], v[136:139]
	v_mfma_f32_16x16x32_bf16 v[128:131], v[108:111], v[12:15], v[128:131]
	s_waitcnt lgkmcnt(0)
	v_mfma_f32_16x16x32_bf16 v[144:147], v[76:79], v[12:15], v[132:135]
	s_nop 3
	v_max3_f32 v132, v124, v125, v126
	v_mfma_f32_16x16x32_bf16 v[138:141], v[88:91], v[12:15], v[136:139]
	v_max3_f32 v133, v127, v128, v129
	v_max3_f32 v132, v132, v130, v131
	v_max3_f32 v134, v144, v145, v146
	v_max3_f32 v132, v132, v133, v134
	s_nop 3
	v_max3_f32 v133, v138, v139, v140
	v_max3_f32 v132, v132, v133, v141
	v_max_f32_e32 v132, v132, v147
	v_cmp_lt_f32_e32 vcc, s34, v132
	s_cbranch_vccz .LBB0_946
	v_and_b32_e32 v134, 64, v251
	v_xor_b32_e32 v133, 16, v251
	v_add_u32_e32 v134, 64, v134
	v_cmp_lt_i32_e32 vcc, v133, v134
	s_nop 1
	v_cndmask_b32_e32 v133, v251, v133, vcc
	v_lshlrev_b32_e32 v133, 2, v133
	ds_bpermute_b32 v133, v133, v132
	v_max_f32_e32 v132, v132, v132
	s_waitcnt lgkmcnt(0)
	v_max_f32_e32 v133, v133, v133
	v_max_f32_e32 v132, v132, v133
	v_xor_b32_e32 v133, 32, v251
	v_cmp_lt_i32_e32 vcc, v133, v134
	s_nop 1
	v_cndmask_b32_e32 v133, v251, v133, vcc
	v_lshlrev_b32_e32 v133, 2, v133
	ds_bpermute_b32 v133, v133, v132
	s_waitcnt lgkmcnt(0)
	v_max3_f32 v133, v132, v133, 0
	v_exp_f32_e64 v132, -v133
	v_add_f32_e32 v203, v203, v133
	v_sub_f32_e32 v124, v124, v133
	v_sub_f32_e32 v125, v125, v133
	v_mul_f32_e32 v200, v200, v132
	v_pk_mul_f32 v[62:63], v[62:63], v[132:133] op_sel_hi:[1,0]
	v_pk_mul_f32 v[60:61], v[60:61], v[132:133] op_sel_hi:[1,0]
	v_pk_mul_f32 v[50:51], v[50:51], v[132:133] op_sel_hi:[1,0]
	v_pk_mul_f32 v[48:49], v[48:49], v[132:133] op_sel_hi:[1,0]
	v_pk_mul_f32 v[74:75], v[74:75], v[132:133] op_sel_hi:[1,0]
	v_pk_mul_f32 v[72:73], v[72:73], v[132:133] op_sel_hi:[1,0]
	v_pk_mul_f32 v[70:71], v[70:71], v[132:133] op_sel_hi:[1,0]
	v_pk_mul_f32 v[68:69], v[68:69], v[132:133] op_sel_hi:[1,0]
	v_sub_f32_e32 v126, v126, v133
	v_sub_f32_e32 v127, v127, v133
	v_sub_f32_e32 v128, v128, v133
	v_sub_f32_e32 v129, v129, v133
	v_sub_f32_e32 v130, v130, v133
	v_sub_f32_e32 v131, v131, v133
	v_sub_f32_e32 v138, v138, v133
	v_sub_f32_e32 v139, v139, v133
	v_sub_f32_e32 v140, v140, v133
	v_sub_f32_e32 v141, v141, v133
	v_sub_f32_e32 v144, v144, v133
	v_sub_f32_e32 v145, v145, v133
	v_sub_f32_e32 v146, v146, v133
	v_sub_f32_e32 v147, v147, v133
; #define MFMA16(a, b, c) __builtin_amdgcn_mfma_f32_16x16x32_bf16((a), (b), (c), 0, 0, 0)
; DI void attn_phase(const Params& p, unsigned char* smem) {
;     ...
;                     for (int qs = 0; qs < 2; ++qs) {
;                         f32x4 st[4];
;                         const float nm = -mrow[qs];
; #pragma unroll
;                         for (int kk = 0; kk < 4; ++kk) {
;                             st[kk] = (f32x4){nm, nm, nm, nm};
; #pragma unroll
;                             for (int s = 0; s < 3; ++s) st[kk] = MFMA16(kf[kk][s], qf[qs][s], st[kk]);
;                         }
;                         float mx = fmaxf(fmaxf(st[0][0], st[0][1]), fmaxf(st[0][2], st[0][3]));
; #pragma unroll
;                         for (int kk = 1; kk < 4; ++kk) mx = fmaxf(mx, fmaxf(fmaxf(st[kk][0], st[kk][1]), fmaxf(st[kk][2], st[kk][3])));
;                         const bool first = (st_ == 0 && hf == 0);
;                         if (first || __any(mx > 6.f)) {
;                             mx = fmaxf(mx, __shfl_xor(mx, 16)); mx = fmaxf(mx, __shfl_xor(mx, 32));
;                             const float shift = first ? mx : fmaxf(mx, 0.f);
;                             const float al = first ? 1.f : __builtin_amdgcn_exp2f(-shift);
;                             mrow[qs] += shift; lrow[qs] *= al;
; #pragma unroll
;                             for (int dt = 0; dt < 4; ++dt) ot[dt][qs] *= al;
; #pragma unroll
;                             for (int kk = 0; kk < 4; ++kk)
; #pragma unroll
;                                 for (int e = 0; e < 4; ++e) st[kk][e] -= shift;
;                         }
;                         float rs = 0.f;
; #pragma unroll
;                         for (int kk = 0; kk < 4; ++kk)
; #pragma unroll
;                             for (int e = 0; e < 4; ++e) { const float pv = __builtin_amdgcn_exp2f(st[kk][e]); st[kk][e] = pv; rs += pv; }
;                         lrow[qs] += rs;
; #pragma unroll
;                         for (int s2 = 0; s2 < 2; ++s2) {
;                             uint4 u; u.x = pack2(st[2 * s2][0], st[2 * s2][1]); u.y = pack2(st[2 * s2][2], st[2 * s2][3]);
;                             u.z = pack2(st[2 * s2 + 1][0], st[2 * s2 + 1][1]); u.w = pack2(st[2 * s2 + 1][2], st[2 * s2 + 1][3]);
;                             const bf16x8 pf = asbf(u);
; #pragma unroll
;                             for (int dt = 0; dt < 4; ++dt) {
.LBB0_946:
	v_add3_u32 v132, s19, v219, v217
	v_exp_f32_e32 v236, v128
	v_add_u32_e32 v142, 0x7000, v132
	v_add3_u32 v128, s19, v220, v217
	v_add3_u32 v132, s19, v221, v217
	v_add3_u32 v136, s19, v222, v217
	v_add_u32_e32 v152, 0x7000, v128
	v_add_u32_e32 v153, 0x7000, v132
	v_add_u32_e32 v154, 0x7000, v136
	v_exp_f32_e32 v232, v124
	v_exp_f32_e32 v233, v125
	v_exp_f32_e32 v234, v126
	v_exp_f32_e32 v235, v127
	v_exp_f32_e32 v237, v129
	v_exp_f32_e32 v238, v130
	v_exp_f32_e32 v239, v131
	ds_read2_b64 v[124:127], v142 offset1:4
	v_exp_f32_e32 v240, v138
	ds_read2_b64 v[128:131], v152 offset1:4
	ds_read2_b64 v[132:135], v153 offset1:4
	v_exp_f32_e32 v241, v139
	ds_read2_b64 v[136:139], v154 offset1:4
	v_cvt_pk_bf16_f32 v148, v232, v233
	v_cvt_pk_bf16_f32 v149, v234, v235
	v_cvt_pk_bf16_f32 v150, v236, v237
	v_cvt_pk_bf16_f32 v151, v238, v239
	v_exp_f32_e32 v242, v140
	v_exp_f32_e32 v243, v141
	s_waitcnt lgkmcnt(3)
	v_mfma_f32_16x16x32_bf16 v[60:63], v[124:127], v[148:151], v[60:63]
	v_exp_f32_e32 v244, v144
	ds_read2_b64 v[140:143], v142 offset0:8 offset1:12
	v_exp_f32_e32 v245, v145
	s_waitcnt lgkmcnt(3)
	v_mfma_f32_16x16x32_bf16 v[48:51], v[128:131], v[148:151], v[48:51]
	v_exp_f32_e32 v246, v146
	v_exp_f32_e32 v247, v147
	ds_read2_b64 v[144:147], v152 offset0:8 offset1:12
	s_waitcnt lgkmcnt(3)
	v_mfma_f32_16x16x32_bf16 v[72:75], v[132:135], v[148:151], v[72:75]
	v_cvt_pk_bf16_f32 v158, v240, v241
	v_cvt_pk_bf16_f32 v159, v242, v243
	v_cvt_pk_bf16_f32 v160, v244, v245
	s_waitcnt lgkmcnt(2)
	v_mfma_f32_16x16x32_bf16 v[68:71], v[136:139], v[148:151], v[68:71]
	ds_read2_b64 v[148:151], v153 offset0:8 offset1:12
	ds_read2_b64 v[152:155], v154 offset0:8 offset1:12
	v_cvt_pk_bf16_f32 v161, v246, v247
	s_waitcnt lgkmcnt(3)
	s_nop 0
	v_mfma_f32_16x16x32_bf16 v[60:63], v[140:143], v[158:161], v[60:63]
	s_waitcnt lgkmcnt(2)
	v_mfma_f32_16x16x32_bf16 v[48:51], v[144:147], v[158:161], v[48:51]
	s_waitcnt lgkmcnt(1)
	v_mfma_f32_16x16x32_bf16 v[72:75], v[148:151], v[158:161], v[72:75]
	s_waitcnt lgkmcnt(0)
	v_mfma_f32_16x16x32_bf16 v[68:71], v[152:155], v[158:161], v[68:71]
	v_xor_b32_e32 v158, 0x80000000, v202
	v_mov_b32_e32 v159, v158
	v_mov_b32_e32 v160, v158
	v_mov_b32_e32 v161, v158
	s_nop 1
	v_mfma_f32_16x16x32_bf16 v[100:103], v[100:103], v[8:11], v[158:161]
	v_mfma_f32_16x16x32_bf16 v[112:115], v[112:115], v[8:11], v[158:161]
	v_mfma_f32_16x16x32_bf16 v[96:99], v[96:99], v[8:11], v[158:161]
	v_mfma_f32_16x16x32_bf16 v[84:87], v[84:87], v[8:11], v[158:161]
	v_mfma_f32_16x16x32_bf16 v[100:103], v[104:107], v[20:23], v[100:103]
	v_mfma_f32_16x16x32_bf16 v[112:115], v[116:119], v[20:23], v[112:115]
	v_mfma_f32_16x16x32_bf16 v[92:95], v[92:95], v[20:23], v[96:99]
	v_mfma_f32_16x16x32_bf16 v[80:83], v[80:83], v[20:23], v[84:87]
	v_mfma_f32_16x16x32_bf16 v[100:103], v[108:111], v[16:19], v[100:103]
	v_mfma_f32_16x16x32_bf16 v[112:115], v[120:123], v[16:19], v[112:115]
	v_mfma_f32_16x16x32_bf16 v[88:91], v[88:91], v[16:19], v[92:95]
	v_mfma_f32_16x16x32_bf16 v[76:79], v[76:79], v[16:19], v[80:83]
	s_nop 4
	v_max3_f32 v93, v100, v101, v102
	v_max3_f32 v94, v103, v112, v113
	v_max3_f32 v96, v114, v115, v88
	v_max3_f32 v93, v93, v94, v96
	v_max3_f32 v94, v89, v90, v91
	v_max3_f32 v96, v76, v77, v78
	v_max3_f32 v93, v93, v94, v96
	v_max_f32_e32 v80, v93, v79
	v_cmp_lt_f32_e32 vcc, s34, v80
	s_cbranch_vccz .LBB0_948
	v_and_b32_e32 v82, 64, v251
	v_xor_b32_e32 v81, 16, v251
	v_add_u32_e32 v82, 64, v82
	v_cmp_lt_i32_e32 vcc, v81, v82
	s_nop 1
	v_cndmask_b32_e32 v81, v251, v81, vcc
	v_lshlrev_b32_e32 v81, 2, v81
	ds_bpermute_b32 v81, v81, v80
	v_max_f32_e32 v80, v80, v80
	s_waitcnt lgkmcnt(0)
	v_max_f32_e32 v81, v81, v81
	v_max_f32_e32 v80, v80, v81
	v_xor_b32_e32 v81, 32, v251
	v_cmp_lt_i32_e32 vcc, v81, v82
	s_nop 1
	v_cndmask_b32_e32 v81, v251, v81, vcc
	v_lshlrev_b32_e32 v81, 2, v81
	ds_bpermute_b32 v81, v81, v80
	s_waitcnt lgkmcnt(0)
	v_max3_f32 v81, v80, v81, 0
	v_exp_f32_e64 v80, -v81
	v_add_f32_e32 v202, v202, v81
	v_sub_f32_e32 v112, v112, v81
	v_sub_f32_e32 v113, v113, v81
	v_mul_f32_e32 v201, v201, v80
	v_pk_mul_f32 v[66:67], v[66:67], v[80:81] op_sel_hi:[1,0]
	v_pk_mul_f32 v[64:65], v[64:65], v[80:81] op_sel_hi:[1,0]
	v_pk_mul_f32 v[58:59], v[58:59], v[80:81] op_sel_hi:[1,0]
	v_pk_mul_f32 v[56:57], v[56:57], v[80:81] op_sel_hi:[1,0]
	v_pk_mul_f32 v[54:55], v[54:55], v[80:81] op_sel_hi:[1,0]
	v_pk_mul_f32 v[52:53], v[52:53], v[80:81] op_sel_hi:[1,0]
	v_pk_mul_f32 v[46:47], v[46:47], v[80:81] op_sel_hi:[1,0]
	v_pk_mul_f32 v[44:45], v[44:45], v[80:81] op_sel_hi:[1,0]
	v_sub_f32_e32 v114, v114, v81
	v_sub_f32_e32 v115, v115, v81
	v_sub_f32_e32 v100, v100, v81
	v_sub_f32_e32 v101, v101, v81
	v_sub_f32_e32 v102, v102, v81
	v_sub_f32_e32 v103, v103, v81
	v_sub_f32_e32 v88, v88, v81
	v_sub_f32_e32 v89, v89, v81
	v_sub_f32_e32 v90, v90, v81
	v_sub_f32_e32 v91, v91, v81
	v_sub_f32_e32 v76, v76, v81
	v_sub_f32_e32 v77, v77, v81
	v_sub_f32_e32 v78, v78, v81
	v_sub_f32_e32 v79, v79, v81

; DI void attn_phase(const Params& p, unsigned char* smem) {
;     ...
;                         const float nm = -mrow[qs];
; #pragma unroll
;                         for (int kk = 0; kk < 4; ++kk) {
;                             st[kk] = (f32x4){nm, nm, nm, nm};
; #pragma unroll
;                             for (int s = 0; s < 3; ++s) st[kk] = MFMA16(kf[kk][s], qf[qs][s], st[kk]);
;                         }
;                         float mx = fmaxf(fmaxf(st[0][0], st[0][1]), fmaxf(st[0][2], st[0][3]));
; #pragma unroll
;                         for (int kk = 1; kk < 4; ++kk) mx = fmaxf(mx, fmaxf(fmaxf(st[kk][0], st[kk][1]), fmaxf(st[kk][2], st[kk][3])));
;                         const bool first = (st_ == 0 && hf == 0);
;                         if (first || __any(mx > 6.f)) {
;                             mx = fmaxf(mx, __shfl_xor(mx, 16)); mx = fmaxf(mx, __shfl_xor(mx, 32));
;                             const float shift = first ? mx : fmaxf(mx, 0.f);
;                             const float al = first ? 1.f : __builtin_amdgcn_exp2f(-shift);
;                             mrow[qs] += shift; lrow[qs] *= al;
; #pragma unroll
;                             for (int dt = 0; dt < 4; ++dt) ot[dt][qs] *= al;
; #pragma unroll
;                             for (int kk = 0; kk < 4; ++kk)
; #pragma unroll
;                                 for (int e = 0; e < 4; ++e) st[kk][e] -= shift;
;                         }
;                         float rs = 0.f;
; #pragma unroll
;                         for (int kk = 0; kk < 4; ++kk)
; #pragma unroll
;                             for (int e = 0; e < 4; ++e) { const float pv = __builtin_amdgcn_exp2f(st[kk][e]); st[kk][e] = pv; rs += pv; }
;                         lrow[qs] += rs;
; #pragma unroll
;                         for (int s2 = 0; s2 < 2; ++s2) {
;                             uint4 u; u.x = pack2(st[2 * s2][0], st[2 * s2][1]); u.y = pack2(st[2 * s2][2], st[2 * s2][3]);
;                             u.z = pack2(st[2 * s2 + 1][0], st[2 * s2 + 1][1]); u.w = pack2(st[2 * s2 + 1][2], st[2 * s2 + 1][3]);
;                             const bf16x8 pf = asbf(u);
; #pragma unroll
;                             for (int dt = 0; dt < 4; ++dt) {
;                                 const uint2 a = *(const uint2*)(sV + (16 * dt + fr) * VST + 32 * s2 + 4 * g), b = *(const uint2*)(sV + (16 * dt + fr) * VST + 32 * s2 + 16 + 4 * g);
.LBB0_952:
	v_add3_u32 v132, s19, v219, v217
	v_exp_f32_e32 v235, v128
	v_add_u32_e32 v142, 0x7000, v132
	v_add3_u32 v128, s19, v220, v217
	v_add3_u32 v132, s19, v221, v217
	v_add3_u32 v136, s19, v222, v217
	v_add_u32_e32 v152, 0x7000, v128
	v_add_u32_e32 v153, 0x7000, v132
	v_add_u32_e32 v154, 0x7000, v136
	v_exp_f32_e32 v231, v124
	v_exp_f32_e32 v232, v125
	v_exp_f32_e32 v233, v126
	v_exp_f32_e32 v234, v127
	v_exp_f32_e32 v236, v129
	v_exp_f32_e32 v237, v130
	v_exp_f32_e32 v238, v131
	ds_read2_b64 v[124:127], v142 offset0:16 offset1:20
	v_exp_f32_e32 v239, v138
	ds_read2_b64 v[128:131], v152 offset0:16 offset1:20
	ds_read2_b64 v[132:135], v153 offset0:16 offset1:20
	v_exp_f32_e32 v240, v139
	ds_read2_b64 v[136:139], v154 offset0:16 offset1:20
	v_cvt_pk_bf16_f32 v148, v231, v232
	v_cvt_pk_bf16_f32 v149, v233, v234
	v_cvt_pk_bf16_f32 v150, v235, v236
	v_cvt_pk_bf16_f32 v151, v237, v238
	v_exp_f32_e32 v241, v140
	v_exp_f32_e32 v242, v141
	s_waitcnt lgkmcnt(3)
	v_mfma_f32_16x16x32_bf16 v[60:63], v[124:127], v[148:151], v[60:63]
	v_exp_f32_e32 v243, v144
	ds_read2_b64 v[140:143], v142 offset0:24 offset1:28
	v_exp_f32_e32 v244, v145
	s_waitcnt lgkmcnt(3)
	v_mfma_f32_16x16x32_bf16 v[48:51], v[128:131], v[148:151], v[48:51]
	v_exp_f32_e32 v245, v146
	v_exp_f32_e32 v246, v147
	ds_read2_b64 v[144:147], v152 offset0:24 offset1:28
	s_waitcnt lgkmcnt(3)
	v_mfma_f32_16x16x32_bf16 v[72:75], v[132:135], v[148:151], v[72:75]
	v_cvt_pk_bf16_f32 v158, v239, v240
	v_cvt_pk_bf16_f32 v159, v241, v242
	v_cvt_pk_bf16_f32 v160, v243, v244
	s_waitcnt lgkmcnt(2)
	v_mfma_f32_16x16x32_bf16 v[68:71], v[136:139], v[148:151], v[68:71]
	ds_read2_b64 v[148:151], v153 offset0:24 offset1:28
	ds_read2_b64 v[152:155], v154 offset0:24 offset1:28
	v_cvt_pk_bf16_f32 v161, v245, v246
	s_waitcnt lgkmcnt(3)
	s_nop 0
	v_mfma_f32_16x16x32_bf16 v[60:63], v[140:143], v[158:161], v[60:63]
	s_waitcnt lgkmcnt(2)
	v_mfma_f32_16x16x32_bf16 v[48:51], v[144:147], v[158:161], v[48:51]
	s_waitcnt lgkmcnt(1)
	v_mfma_f32_16x16x32_bf16 v[72:75], v[148:151], v[158:161], v[72:75]
	s_waitcnt lgkmcnt(0)
	v_mfma_f32_16x16x32_bf16 v[68:71], v[152:155], v[158:161], v[68:71]
	v_xor_b32_e32 v158, 0x80000000, v202
	v_mov_b32_e32 v159, v158
	v_mov_b32_e32 v160, v158
	v_mov_b32_e32 v161, v158
	s_nop 1
	v_mfma_f32_16x16x32_bf16 v[100:103], v[100:103], v[8:11], v[158:161]
	v_mfma_f32_16x16x32_bf16 v[112:115], v[112:115], v[8:11], v[158:161]
	v_mfma_f32_16x16x32_bf16 v[96:99], v[96:99], v[8:11], v[158:161]
	v_mfma_f32_16x16x32_bf16 v[84:87], v[84:87], v[8:11], v[158:161]
	v_mfma_f32_16x16x32_bf16 v[100:103], v[104:107], v[20:23], v[100:103]
	v_mfma_f32_16x16x32_bf16 v[112:115], v[116:119], v[20:23], v[112:115]
	v_mfma_f32_16x16x32_bf16 v[92:95], v[92:95], v[20:23], v[96:99]
	v_mfma_f32_16x16x32_bf16 v[80:83], v[80:83], v[20:23], v[84:87]
	v_mfma_f32_16x16x32_bf16 v[100:103], v[108:111], v[16:19], v[100:103]
	v_mfma_f32_16x16x32_bf16 v[112:115], v[120:123], v[16:19], v[112:115]
	v_mfma_f32_16x16x32_bf16 v[88:91], v[88:91], v[16:19], v[92:95]
	v_mfma_f32_16x16x32_bf16 v[76:79], v[76:79], v[16:19], v[80:83]
	s_nop 4
	v_max3_f32 v93, v100, v101, v102
	v_max3_f32 v94, v103, v112, v113
	v_max3_f32 v96, v114, v115, v88
	v_max3_f32 v93, v93, v94, v96
	v_max3_f32 v94, v89, v90, v91
	v_max3_f32 v96, v76, v77, v78
	v_max3_f32 v93, v93, v94, v96
	v_max_f32_e32 v80, v93, v79
	v_cmp_lt_f32_e32 vcc, s34, v80
	s_cbranch_vccz .LBB0_954
	v_and_b32_e32 v82, 64, v251
	v_xor_b32_e32 v81, 16, v251
	v_add_u32_e32 v82, 64, v82
	v_cmp_lt_i32_e32 vcc, v81, v82
	s_nop 1
	v_cndmask_b32_e32 v81, v251, v81, vcc
	v_lshlrev_b32_e32 v81, 2, v81
	ds_bpermute_b32 v81, v81, v80
	v_max_f32_e32 v80, v80, v80
	s_waitcnt lgkmcnt(0)
	v_max_f32_e32 v81, v81, v81
	v_max_f32_e32 v80, v80, v81
	v_xor_b32_e32 v81, 32, v251
	v_cmp_lt_i32_e32 vcc, v81, v82
	s_nop 1
	v_cndmask_b32_e32 v81, v251, v81, vcc
	v_lshlrev_b32_e32 v81, 2, v81
	ds_bpermute_b32 v81, v81, v80
	s_waitcnt lgkmcnt(0)
	v_max3_f32 v81, v80, v81, 0
	v_exp_f32_e64 v80, -v81
	v_add_f32_e32 v202, v202, v81
	v_sub_f32_e32 v112, v112, v81
	v_sub_f32_e32 v113, v113, v81
	v_mul_f32_e32 v201, v201, v80
	v_pk_mul_f32 v[66:67], v[66:67], v[80:81] op_sel_hi:[1,0]
	v_pk_mul_f32 v[64:65], v[64:65], v[80:81] op_sel_hi:[1,0]
	v_pk_mul_f32 v[58:59], v[58:59], v[80:81] op_sel_hi:[1,0]
	v_pk_mul_f32 v[56:57], v[56:57], v[80:81] op_sel_hi:[1,0]
	v_pk_mul_f32 v[54:55], v[54:55], v[80:81] op_sel_hi:[1,0]
	v_pk_mul_f32 v[52:53], v[52:53], v[80:81] op_sel_hi:[1,0]
	v_pk_mul_f32 v[46:47], v[46:47], v[80:81] op_sel_hi:[1,0]
	v_pk_mul_f32 v[44:45], v[44:45], v[80:81] op_sel_hi:[1,0]
	v_sub_f32_e32 v114, v114, v81
	v_sub_f32_e32 v115, v115, v81
	v_sub_f32_e32 v100, v100, v81
	v_sub_f32_e32 v101, v101, v81
	v_sub_f32_e32 v102, v102, v81
	v_sub_f32_e32 v103, v103, v81
	v_sub_f32_e32 v88, v88, v81
	v_sub_f32_e32 v89, v89, v81
	v_sub_f32_e32 v90, v90, v81
	v_sub_f32_e32 v91, v91, v81
	v_sub_f32_e32 v76, v76, v81
	v_sub_f32_e32 v77, v77, v81
	v_sub_f32_e32 v78, v78, v81
	v_sub_f32_e32 v79, v79, v81
